# double-tile K-loop: B DMA issued after the fragment reads, A DMA groups woven between the MFMAs of the second half-step
# baseline (speedup 1.0000x reference)
.Lg2_k:
	s_waitcnt vmcnt(0)
	s_barrier
	ds_read_b128 v[148:151], v78 offset:0
	ds_read_b128 v[152:155], v78 offset:2048
	ds_read_b128 v[156:159], v78 offset:4096
	ds_read_b128 v[160:163], v78 offset:6144
	ds_read_b128 v[188:191], v79 offset:32768
	ds_read_b128 v[192:195], v79 offset:34816
	ds_read_b128 v[208:211], v79 offset:36864
	ds_read_b128 v[212:215], v79 offset:38912
	ds_read_b128 v[164:167], v78 offset:16384
	ds_read_b128 v[168:171], v78 offset:18432
	ds_read_b128 v[174:177], v78 offset:20480
	ds_read_b128 v[182:185], v78 offset:22528
	s_add_i32 m0, s58, 0xc000
	s_nop 0
	global_load_lds_dwordx4 v74, s[56:57]
	s_add_i32 m0, s58, 0xd000
	s_nop 0
	global_load_lds_dwordx4 v75, s[56:57]
	s_add_i32 m0, s58, 0xe000
	s_nop 0
	global_load_lds_dwordx4 v76, s[56:57]
	s_add_i32 m0, s58, 0xf000
	s_nop 0
	global_load_lds_dwordx4 v77, s[56:57]
	s_add_u32 s56, s56, 0x80
	s_addc_u32 s57, s57, 0
	s_setprio 1
	s_waitcnt lgkmcnt(4)
	v_mfma_f32_16x16x32_bf16 v[62:65], v[188:191], v[148:151], v[62:65]
	v_mfma_f32_16x16x32_bf16 v[58:61], v[192:195], v[148:151], v[58:61]
	v_mfma_f32_16x16x32_bf16 v[54:57], v[208:211], v[148:151], v[54:57]
	v_mfma_f32_16x16x32_bf16 v[50:53], v[212:215], v[148:151], v[50:53]
	v_mfma_f32_16x16x32_bf16 v[46:49], v[188:191], v[152:155], v[46:49]
	v_mfma_f32_16x16x32_bf16 v[42:45], v[192:195], v[152:155], v[42:45]
	v_mfma_f32_16x16x32_bf16 v[38:41], v[208:211], v[152:155], v[38:41]
	v_mfma_f32_16x16x32_bf16 v[34:37], v[212:215], v[152:155], v[34:37]
	v_mfma_f32_16x16x32_bf16 v[30:33], v[188:191], v[156:159], v[30:33]
	v_mfma_f32_16x16x32_bf16 v[26:29], v[192:195], v[156:159], v[26:29]
	v_mfma_f32_16x16x32_bf16 v[22:25], v[208:211], v[156:159], v[22:25]
	v_mfma_f32_16x16x32_bf16 v[18:21], v[212:215], v[156:159], v[18:21]
	v_mfma_f32_16x16x32_bf16 v[14:17], v[188:191], v[160:163], v[14:17]
	v_mfma_f32_16x16x32_bf16 v[10:13], v[192:195], v[160:163], v[10:13]
	v_mfma_f32_16x16x32_bf16 v[6:9], v[208:211], v[160:163], v[6:9]
	v_mfma_f32_16x16x32_bf16 v[2:5], v[212:215], v[160:163], v[2:5]
	s_waitcnt lgkmcnt(0)
	v_mfma_f32_16x16x32_bf16 v[66:69], v[188:191], v[164:167], v[66:69]
	v_mfma_f32_16x16x32_bf16 v[70:73], v[192:195], v[164:167], v[70:73]
	v_mfma_f32_16x16x32_bf16 v[82:85], v[208:211], v[164:167], v[82:85]
	v_mfma_f32_16x16x32_bf16 v[88:91], v[212:215], v[164:167], v[88:91]
	v_mfma_f32_16x16x32_bf16 v[92:95], v[188:191], v[168:171], v[92:95]
	v_mfma_f32_16x16x32_bf16 v[96:99], v[192:195], v[168:171], v[96:99]
	v_mfma_f32_16x16x32_bf16 v[100:103], v[208:211], v[168:171], v[100:103]
	v_mfma_f32_16x16x32_bf16 v[106:109], v[212:215], v[168:171], v[106:109]
	v_mfma_f32_16x16x32_bf16 v[110:113], v[188:191], v[174:177], v[110:113]
	v_mfma_f32_16x16x32_bf16 v[114:117], v[192:195], v[174:177], v[114:117]
	v_mfma_f32_16x16x32_bf16 v[118:121], v[208:211], v[174:177], v[118:121]
	v_mfma_f32_16x16x32_bf16 v[122:125], v[212:215], v[174:177], v[122:125]
	v_mfma_f32_16x16x32_bf16 v[126:129], v[188:191], v[182:185], v[126:129]
	v_mfma_f32_16x16x32_bf16 v[136:139], v[192:195], v[182:185], v[136:139]
	v_mfma_f32_16x16x32_bf16 v[140:143], v[208:211], v[182:185], v[140:143]
	v_mfma_f32_16x16x32_bf16 v[144:147], v[212:215], v[182:185], v[144:147]
	s_setprio 0
	ds_read_b128 v[148:151], v80 offset:0
	ds_read_b128 v[152:155], v80 offset:2048
	ds_read_b128 v[156:159], v80 offset:4096
	ds_read_b128 v[160:163], v80 offset:6144
	ds_read_b128 v[188:191], v81 offset:32768
	ds_read_b128 v[192:195], v81 offset:34816
	ds_read_b128 v[208:211], v81 offset:36864
	ds_read_b128 v[212:215], v81 offset:38912
	ds_read_b128 v[164:167], v80 offset:16384
	ds_read_b128 v[168:171], v80 offset:18432
	ds_read_b128 v[174:177], v80 offset:20480
	ds_read_b128 v[182:185], v80 offset:22528
	s_waitcnt lgkmcnt(0)
	s_barrier
	v_mfma_f32_16x16x32_bf16 v[62:65], v[188:191], v[148:151], v[62:65]
	s_add_i32 m0, s58, 0x0
	s_nop 0
	global_load_lds_dwordx4 v74, s[50:51]
	v_mfma_f32_16x16x32_bf16 v[58:61], v[192:195], v[148:151], v[58:61]
	s_add_i32 m0, s58, 0x1000
	s_nop 0
	global_load_lds_dwordx4 v75, s[50:51]
	v_mfma_f32_16x16x32_bf16 v[54:57], v[208:211], v[148:151], v[54:57]
	s_add_i32 m0, s58, 0x2000
	s_nop 0
	global_load_lds_dwordx4 v76, s[50:51]
	v_mfma_f32_16x16x32_bf16 v[50:53], v[212:215], v[148:151], v[50:53]
	s_add_i32 m0, s58, 0x3000
	s_nop 0
	global_load_lds_dwordx4 v77, s[50:51]
	v_mfma_f32_16x16x32_bf16 v[46:49], v[188:191], v[152:155], v[46:49]
	s_add_i32 m0, s58, 0x4000
	s_nop 0
	global_load_lds_dwordx4 v74, s[52:53]
	v_mfma_f32_16x16x32_bf16 v[42:45], v[192:195], v[152:155], v[42:45]
	s_add_i32 m0, s58, 0x5000
	s_nop 0
	global_load_lds_dwordx4 v75, s[52:53]
	v_mfma_f32_16x16x32_bf16 v[38:41], v[208:211], v[152:155], v[38:41]
	s_add_i32 m0, s58, 0x6000
	s_nop 0
	global_load_lds_dwordx4 v76, s[52:53]
	v_mfma_f32_16x16x32_bf16 v[34:37], v[212:215], v[152:155], v[34:37]
	s_add_i32 m0, s58, 0x7000
	s_nop 0
	global_load_lds_dwordx4 v77, s[52:53]
	v_mfma_f32_16x16x32_bf16 v[30:33], v[188:191], v[156:159], v[30:33]
	s_add_u32 s50, s50, 0x80
	s_addc_u32 s51, s51, 0
	v_mfma_f32_16x16x32_bf16 v[26:29], v[192:195], v[156:159], v[26:29]
	s_add_u32 s52, s52, 0x80
	s_addc_u32 s53, s53, 0
	v_mfma_f32_16x16x32_bf16 v[22:25], v[208:211], v[156:159], v[22:25]
	v_mfma_f32_16x16x32_bf16 v[18:21], v[212:215], v[156:159], v[18:21]
	v_mfma_f32_16x16x32_bf16 v[14:17], v[188:191], v[160:163], v[14:17]
	v_mfma_f32_16x16x32_bf16 v[10:13], v[192:195], v[160:163], v[10:13]
	v_mfma_f32_16x16x32_bf16 v[6:9], v[208:211], v[160:163], v[6:9]
	v_mfma_f32_16x16x32_bf16 v[2:5], v[212:215], v[160:163], v[2:5]
	v_mfma_f32_16x16x32_bf16 v[66:69], v[188:191], v[164:167], v[66:69]
	v_mfma_f32_16x16x32_bf16 v[70:73], v[192:195], v[164:167], v[70:73]
	v_mfma_f32_16x16x32_bf16 v[82:85], v[208:211], v[164:167], v[82:85]
	v_mfma_f32_16x16x32_bf16 v[88:91], v[212:215], v[164:167], v[88:91]
	v_mfma_f32_16x16x32_bf16 v[92:95], v[188:191], v[168:171], v[92:95]
	v_mfma_f32_16x16x32_bf16 v[96:99], v[192:195], v[168:171], v[96:99]
	v_mfma_f32_16x16x32_bf16 v[100:103], v[208:211], v[168:171], v[100:103]
	v_mfma_f32_16x16x32_bf16 v[106:109], v[212:215], v[168:171], v[106:109]
	v_mfma_f32_16x16x32_bf16 v[110:113], v[188:191], v[174:177], v[110:113]
	v_mfma_f32_16x16x32_bf16 v[114:117], v[192:195], v[174:177], v[114:117]
	v_mfma_f32_16x16x32_bf16 v[118:121], v[208:211], v[174:177], v[118:121]
	v_mfma_f32_16x16x32_bf16 v[122:125], v[212:215], v[174:177], v[122:125]
	v_mfma_f32_16x16x32_bf16 v[126:129], v[188:191], v[182:185], v[126:129]
	v_mfma_f32_16x16x32_bf16 v[136:139], v[192:195], v[182:185], v[136:139]
	v_mfma_f32_16x16x32_bf16 v[140:143], v[208:211], v[182:185], v[140:143]
	v_mfma_f32_16x16x32_bf16 v[144:147], v[212:215], v[182:185], v[144:147]
	s_waitcnt vmcnt(0)
	s_barrier
	ds_read_b128 v[148:151], v78 offset:0
	ds_read_b128 v[152:155], v78 offset:2048
	ds_read_b128 v[156:159], v78 offset:4096
	ds_read_b128 v[160:163], v78 offset:6144
	ds_read_b128 v[188:191], v79 offset:49152
	ds_read_b128 v[192:195], v79 offset:51200
	ds_read_b128 v[208:211], v79 offset:53248
	ds_read_b128 v[212:215], v79 offset:55296
	ds_read_b128 v[164:167], v78 offset:16384
	ds_read_b128 v[168:171], v78 offset:18432
	ds_read_b128 v[174:177], v78 offset:20480
	ds_read_b128 v[182:185], v78 offset:22528
	s_add_i32 m0, s58, 0x8000
	s_nop 0
	global_load_lds_dwordx4 v74, s[56:57]
	s_add_i32 m0, s58, 0x9000
	s_nop 0
	global_load_lds_dwordx4 v75, s[56:57]
	s_add_i32 m0, s58, 0xa000
	s_nop 0
	global_load_lds_dwordx4 v76, s[56:57]
	s_add_i32 m0, s58, 0xb000
	s_nop 0
	global_load_lds_dwordx4 v77, s[56:57]
	s_add_u32 s56, s56, 0x80
	s_addc_u32 s57, s57, 0
	s_setprio 1
	s_waitcnt lgkmcnt(4)
	v_mfma_f32_16x16x32_bf16 v[62:65], v[188:191], v[148:151], v[62:65]
	v_mfma_f32_16x16x32_bf16 v[58:61], v[192:195], v[148:151], v[58:61]
	v_mfma_f32_16x16x32_bf16 v[54:57], v[208:211], v[148:151], v[54:57]
	v_mfma_f32_16x16x32_bf16 v[50:53], v[212:215], v[148:151], v[50:53]
	v_mfma_f32_16x16x32_bf16 v[46:49], v[188:191], v[152:155], v[46:49]
	v_mfma_f32_16x16x32_bf16 v[42:45], v[192:195], v[152:155], v[42:45]
	v_mfma_f32_16x16x32_bf16 v[38:41], v[208:211], v[152:155], v[38:41]
	v_mfma_f32_16x16x32_bf16 v[34:37], v[212:215], v[152:155], v[34:37]
	v_mfma_f32_16x16x32_bf16 v[30:33], v[188:191], v[156:159], v[30:33]
	v_mfma_f32_16x16x32_bf16 v[26:29], v[192:195], v[156:159], v[26:29]
	v_mfma_f32_16x16x32_bf16 v[22:25], v[208:211], v[156:159], v[22:25]
	v_mfma_f32_16x16x32_bf16 v[18:21], v[212:215], v[156:159], v[18:21]
	v_mfma_f32_16x16x32_bf16 v[14:17], v[188:191], v[160:163], v[14:17]
	v_mfma_f32_16x16x32_bf16 v[10:13], v[192:195], v[160:163], v[10:13]
	v_mfma_f32_16x16x32_bf16 v[6:9], v[208:211], v[160:163], v[6:9]
	v_mfma_f32_16x16x32_bf16 v[2:5], v[212:215], v[160:163], v[2:5]
	s_waitcnt lgkmcnt(0)
	v_mfma_f32_16x16x32_bf16 v[66:69], v[188:191], v[164:167], v[66:69]
	v_mfma_f32_16x16x32_bf16 v[70:73], v[192:195], v[164:167], v[70:73]
	v_mfma_f32_16x16x32_bf16 v[82:85], v[208:211], v[164:167], v[82:85]
	v_mfma_f32_16x16x32_bf16 v[88:91], v[212:215], v[164:167], v[88:91]
	v_mfma_f32_16x16x32_bf16 v[92:95], v[188:191], v[168:171], v[92:95]
	v_mfma_f32_16x16x32_bf16 v[96:99], v[192:195], v[168:171], v[96:99]
	v_mfma_f32_16x16x32_bf16 v[100:103], v[208:211], v[168:171], v[100:103]
	v_mfma_f32_16x16x32_bf16 v[106:109], v[212:215], v[168:171], v[106:109]
	v_mfma_f32_16x16x32_bf16 v[110:113], v[188:191], v[174:177], v[110:113]
	v_mfma_f32_16x16x32_bf16 v[114:117], v[192:195], v[174:177], v[114:117]
	v_mfma_f32_16x16x32_bf16 v[118:121], v[208:211], v[174:177], v[118:121]
	v_mfma_f32_16x16x32_bf16 v[122:125], v[212:215], v[174:177], v[122:125]
	v_mfma_f32_16x16x32_bf16 v[126:129], v[188:191], v[182:185], v[126:129]
	v_mfma_f32_16x16x32_bf16 v[136:139], v[192:195], v[182:185], v[136:139]
	v_mfma_f32_16x16x32_bf16 v[140:143], v[208:211], v[182:185], v[140:143]
	v_mfma_f32_16x16x32_bf16 v[144:147], v[212:215], v[182:185], v[144:147]
	s_setprio 0
	ds_read_b128 v[148:151], v80 offset:0
	ds_read_b128 v[152:155], v80 offset:2048
	ds_read_b128 v[156:159], v80 offset:4096
	ds_read_b128 v[160:163], v80 offset:6144
	ds_read_b128 v[188:191], v81 offset:49152
	ds_read_b128 v[192:195], v81 offset:51200
	ds_read_b128 v[208:211], v81 offset:53248
	ds_read_b128 v[212:215], v81 offset:55296
	ds_read_b128 v[164:167], v80 offset:16384
	ds_read_b128 v[168:171], v80 offset:18432
	ds_read_b128 v[174:177], v80 offset:20480
	ds_read_b128 v[182:185], v80 offset:22528
	s_waitcnt lgkmcnt(0)
	s_barrier
	v_mfma_f32_16x16x32_bf16 v[62:65], v[188:191], v[148:151], v[62:65]
	s_add_i32 m0, s58, 0x0
	s_nop 0
	global_load_lds_dwordx4 v74, s[50:51]
	v_mfma_f32_16x16x32_bf16 v[58:61], v[192:195], v[148:151], v[58:61]
	s_add_i32 m0, s58, 0x1000
	s_nop 0
	global_load_lds_dwordx4 v75, s[50:51]
	v_mfma_f32_16x16x32_bf16 v[54:57], v[208:211], v[148:151], v[54:57]
	s_add_i32 m0, s58, 0x2000
	s_nop 0
	global_load_lds_dwordx4 v76, s[50:51]
	v_mfma_f32_16x16x32_bf16 v[50:53], v[212:215], v[148:151], v[50:53]
	s_add_i32 m0, s58, 0x3000
	s_nop 0
	global_load_lds_dwordx4 v77, s[50:51]
	v_mfma_f32_16x16x32_bf16 v[46:49], v[188:191], v[152:155], v[46:49]
	s_add_i32 m0, s58, 0x4000
	s_nop 0
	global_load_lds_dwordx4 v74, s[52:53]
	v_mfma_f32_16x16x32_bf16 v[42:45], v[192:195], v[152:155], v[42:45]
	s_add_i32 m0, s58, 0x5000
	s_nop 0
	global_load_lds_dwordx4 v75, s[52:53]
	v_mfma_f32_16x16x32_bf16 v[38:41], v[208:211], v[152:155], v[38:41]
	s_add_i32 m0, s58, 0x6000
	s_nop 0
	global_load_lds_dwordx4 v76, s[52:53]
	v_mfma_f32_16x16x32_bf16 v[34:37], v[212:215], v[152:155], v[34:37]
	s_add_i32 m0, s58, 0x7000
	s_nop 0
	global_load_lds_dwordx4 v77, s[52:53]
	v_mfma_f32_16x16x32_bf16 v[30:33], v[188:191], v[156:159], v[30:33]
	s_add_u32 s50, s50, 0x80
	s_addc_u32 s51, s51, 0
	v_mfma_f32_16x16x32_bf16 v[26:29], v[192:195], v[156:159], v[26:29]
	s_add_u32 s52, s52, 0x80
	s_addc_u32 s53, s53, 0
	v_mfma_f32_16x16x32_bf16 v[22:25], v[208:211], v[156:159], v[22:25]
	v_mfma_f32_16x16x32_bf16 v[18:21], v[212:215], v[156:159], v[18:21]
	v_mfma_f32_16x16x32_bf16 v[14:17], v[188:191], v[160:163], v[14:17]
	v_mfma_f32_16x16x32_bf16 v[10:13], v[192:195], v[160:163], v[10:13]
	v_mfma_f32_16x16x32_bf16 v[6:9], v[208:211], v[160:163], v[6:9]
	v_mfma_f32_16x16x32_bf16 v[2:5], v[212:215], v[160:163], v[2:5]
	v_mfma_f32_16x16x32_bf16 v[66:69], v[188:191], v[164:167], v[66:69]
	v_mfma_f32_16x16x32_bf16 v[70:73], v[192:195], v[164:167], v[70:73]
	v_mfma_f32_16x16x32_bf16 v[82:85], v[208:211], v[164:167], v[82:85]
	v_mfma_f32_16x16x32_bf16 v[88:91], v[212:215], v[164:167], v[88:91]
	v_mfma_f32_16x16x32_bf16 v[92:95], v[188:191], v[168:171], v[92:95]
	v_mfma_f32_16x16x32_bf16 v[96:99], v[192:195], v[168:171], v[96:99]
	v_mfma_f32_16x16x32_bf16 v[100:103], v[208:211], v[168:171], v[100:103]
	v_mfma_f32_16x16x32_bf16 v[106:109], v[212:215], v[168:171], v[106:109]
	v_mfma_f32_16x16x32_bf16 v[110:113], v[188:191], v[174:177], v[110:113]
	v_mfma_f32_16x16x32_bf16 v[114:117], v[192:195], v[174:177], v[114:117]
	v_mfma_f32_16x16x32_bf16 v[118:121], v[208:211], v[174:177], v[118:121]
	v_mfma_f32_16x16x32_bf16 v[122:125], v[212:215], v[174:177], v[122:125]
	v_mfma_f32_16x16x32_bf16 v[126:129], v[188:191], v[182:185], v[126:129]
	v_mfma_f32_16x16x32_bf16 v[136:139], v[192:195], v[182:185], v[136:139]
	v_mfma_f32_16x16x32_bf16 v[140:143], v[208:211], v[182:185], v[140:143]
	v_mfma_f32_16x16x32_bf16 v[144:147], v[212:215], v[182:185], v[144:147]
	s_add_i32 s59, s59, -1
	s_cmp_lg_u32 s59, 0
	s_cbranch_scc1 .Lg2_k
	s_waitcnt vmcnt(0)
	s_barrier
	ds_read_b128 v[148:151], v78 offset:0
	ds_read_b128 v[152:155], v78 offset:2048
	ds_read_b128 v[156:159], v78 offset:4096
	ds_read_b128 v[160:163], v78 offset:6144
	ds_read_b128 v[188:191], v79 offset:32768
	ds_read_b128 v[192:195], v79 offset:34816
	ds_read_b128 v[208:211], v79 offset:36864
	ds_read_b128 v[212:215], v79 offset:38912
	ds_read_b128 v[164:167], v78 offset:16384
	ds_read_b128 v[168:171], v78 offset:18432
	ds_read_b128 v[174:177], v78 offset:20480
	ds_read_b128 v[182:185], v78 offset:22528
	s_add_i32 m0, s58, 0xc000
	s_nop 0
	global_load_lds_dwordx4 v74, s[56:57]
	s_add_i32 m0, s58, 0xd000
	s_nop 0
	global_load_lds_dwordx4 v75, s[56:57]
	s_add_i32 m0, s58, 0xe000
	s_nop 0
	global_load_lds_dwordx4 v76, s[56:57]
	s_add_i32 m0, s58, 0xf000
	s_nop 0
	global_load_lds_dwordx4 v77, s[56:57]
	s_add_u32 s56, s56, 0x80
	s_addc_u32 s57, s57, 0
	s_setprio 1
	s_waitcnt lgkmcnt(4)
	v_mfma_f32_16x16x32_bf16 v[62:65], v[188:191], v[148:151], v[62:65]
	v_mfma_f32_16x16x32_bf16 v[58:61], v[192:195], v[148:151], v[58:61]
	v_mfma_f32_16x16x32_bf16 v[54:57], v[208:211], v[148:151], v[54:57]
	v_mfma_f32_16x16x32_bf16 v[50:53], v[212:215], v[148:151], v[50:53]
	v_mfma_f32_16x16x32_bf16 v[46:49], v[188:191], v[152:155], v[46:49]
	v_mfma_f32_16x16x32_bf16 v[42:45], v[192:195], v[152:155], v[42:45]
	v_mfma_f32_16x16x32_bf16 v[38:41], v[208:211], v[152:155], v[38:41]
	v_mfma_f32_16x16x32_bf16 v[34:37], v[212:215], v[152:155], v[34:37]
	v_mfma_f32_16x16x32_bf16 v[30:33], v[188:191], v[156:159], v[30:33]
	v_mfma_f32_16x16x32_bf16 v[26:29], v[192:195], v[156:159], v[26:29]
	v_mfma_f32_16x16x32_bf16 v[22:25], v[208:211], v[156:159], v[22:25]
	v_mfma_f32_16x16x32_bf16 v[18:21], v[212:215], v[156:159], v[18:21]
	v_mfma_f32_16x16x32_bf16 v[14:17], v[188:191], v[160:163], v[14:17]
	v_mfma_f32_16x16x32_bf16 v[10:13], v[192:195], v[160:163], v[10:13]
	v_mfma_f32_16x16x32_bf16 v[6:9], v[208:211], v[160:163], v[6:9]
	v_mfma_f32_16x16x32_bf16 v[2:5], v[212:215], v[160:163], v[2:5]
	s_waitcnt lgkmcnt(0)
	v_mfma_f32_16x16x32_bf16 v[66:69], v[188:191], v[164:167], v[66:69]
	v_mfma_f32_16x16x32_bf16 v[70:73], v[192:195], v[164:167], v[70:73]
	v_mfma_f32_16x16x32_bf16 v[82:85], v[208:211], v[164:167], v[82:85]
	v_mfma_f32_16x16x32_bf16 v[88:91], v[212:215], v[164:167], v[88:91]
	v_mfma_f32_16x16x32_bf16 v[92:95], v[188:191], v[168:171], v[92:95]
	v_mfma_f32_16x16x32_bf16 v[96:99], v[192:195], v[168:171], v[96:99]
	v_mfma_f32_16x16x32_bf16 v[100:103], v[208:211], v[168:171], v[100:103]
	v_mfma_f32_16x16x32_bf16 v[106:109], v[212:215], v[168:171], v[106:109]
	v_mfma_f32_16x16x32_bf16 v[110:113], v[188:191], v[174:177], v[110:113]
	v_mfma_f32_16x16x32_bf16 v[114:117], v[192:195], v[174:177], v[114:117]
	v_mfma_f32_16x16x32_bf16 v[118:121], v[208:211], v[174:177], v[118:121]
	v_mfma_f32_16x16x32_bf16 v[122:125], v[212:215], v[174:177], v[122:125]
	v_mfma_f32_16x16x32_bf16 v[126:129], v[188:191], v[182:185], v[126:129]
	v_mfma_f32_16x16x32_bf16 v[136:139], v[192:195], v[182:185], v[136:139]
	v_mfma_f32_16x16x32_bf16 v[140:143], v[208:211], v[182:185], v[140:143]
	v_mfma_f32_16x16x32_bf16 v[144:147], v[212:215], v[182:185], v[144:147]
	s_setprio 0
	ds_read_b128 v[148:151], v80 offset:0
	ds_read_b128 v[152:155], v80 offset:2048
	ds_read_b128 v[156:159], v80 offset:4096
	ds_read_b128 v[160:163], v80 offset:6144
	ds_read_b128 v[188:191], v81 offset:32768
	ds_read_b128 v[192:195], v81 offset:34816
	ds_read_b128 v[208:211], v81 offset:36864
	ds_read_b128 v[212:215], v81 offset:38912
	ds_read_b128 v[164:167], v80 offset:16384
	ds_read_b128 v[168:171], v80 offset:18432
	ds_read_b128 v[174:177], v80 offset:20480
	ds_read_b128 v[182:185], v80 offset:22528
	s_waitcnt lgkmcnt(0)
	s_barrier
	v_mfma_f32_16x16x32_bf16 v[62:65], v[188:191], v[148:151], v[62:65]
	s_add_i32 m0, s58, 0x0
	s_nop 0
	global_load_lds_dwordx4 v74, s[50:51]
	v_mfma_f32_16x16x32_bf16 v[58:61], v[192:195], v[148:151], v[58:61]
	s_add_i32 m0, s58, 0x1000
	s_nop 0
	global_load_lds_dwordx4 v75, s[50:51]
	v_mfma_f32_16x16x32_bf16 v[54:57], v[208:211], v[148:151], v[54:57]
	s_add_i32 m0, s58, 0x2000
	s_nop 0
	global_load_lds_dwordx4 v76, s[50:51]
	v_mfma_f32_16x16x32_bf16 v[50:53], v[212:215], v[148:151], v[50:53]
	s_add_i32 m0, s58, 0x3000
	s_nop 0
	global_load_lds_dwordx4 v77, s[50:51]
	v_mfma_f32_16x16x32_bf16 v[46:49], v[188:191], v[152:155], v[46:49]
	s_add_i32 m0, s58, 0x4000
	s_nop 0
	global_load_lds_dwordx4 v74, s[52:53]
	v_mfma_f32_16x16x32_bf16 v[42:45], v[192:195], v[152:155], v[42:45]
	s_add_i32 m0, s58, 0x5000
	s_nop 0
	global_load_lds_dwordx4 v75, s[52:53]
	v_mfma_f32_16x16x32_bf16 v[38:41], v[208:211], v[152:155], v[38:41]
	s_add_i32 m0, s58, 0x6000
	s_nop 0
	global_load_lds_dwordx4 v76, s[52:53]
	v_mfma_f32_16x16x32_bf16 v[34:37], v[212:215], v[152:155], v[34:37]
	s_add_i32 m0, s58, 0x7000
	s_nop 0
	global_load_lds_dwordx4 v77, s[52:53]
	v_mfma_f32_16x16x32_bf16 v[30:33], v[188:191], v[156:159], v[30:33]
	s_add_u32 s50, s50, 0x80
	s_addc_u32 s51, s51, 0
	v_mfma_f32_16x16x32_bf16 v[26:29], v[192:195], v[156:159], v[26:29]
	s_add_u32 s52, s52, 0x80
	s_addc_u32 s53, s53, 0
	v_mfma_f32_16x16x32_bf16 v[22:25], v[208:211], v[156:159], v[22:25]
	v_mfma_f32_16x16x32_bf16 v[18:21], v[212:215], v[156:159], v[18:21]
	v_mfma_f32_16x16x32_bf16 v[14:17], v[188:191], v[160:163], v[14:17]
	v_mfma_f32_16x16x32_bf16 v[10:13], v[192:195], v[160:163], v[10:13]
	v_mfma_f32_16x16x32_bf16 v[6:9], v[208:211], v[160:163], v[6:9]
	v_mfma_f32_16x16x32_bf16 v[2:5], v[212:215], v[160:163], v[2:5]
	v_mfma_f32_16x16x32_bf16 v[66:69], v[188:191], v[164:167], v[66:69]
	v_mfma_f32_16x16x32_bf16 v[70:73], v[192:195], v[164:167], v[70:73]
	v_mfma_f32_16x16x32_bf16 v[82:85], v[208:211], v[164:167], v[82:85]
	v_mfma_f32_16x16x32_bf16 v[88:91], v[212:215], v[164:167], v[88:91]
	v_mfma_f32_16x16x32_bf16 v[92:95], v[188:191], v[168:171], v[92:95]
	v_mfma_f32_16x16x32_bf16 v[96:99], v[192:195], v[168:171], v[96:99]
	v_mfma_f32_16x16x32_bf16 v[100:103], v[208:211], v[168:171], v[100:103]
	v_mfma_f32_16x16x32_bf16 v[106:109], v[212:215], v[168:171], v[106:109]
	v_mfma_f32_16x16x32_bf16 v[110:113], v[188:191], v[174:177], v[110:113]
	v_mfma_f32_16x16x32_bf16 v[114:117], v[192:195], v[174:177], v[114:117]
	v_mfma_f32_16x16x32_bf16 v[118:121], v[208:211], v[174:177], v[118:121]
	v_mfma_f32_16x16x32_bf16 v[122:125], v[212:215], v[174:177], v[122:125]
	v_mfma_f32_16x16x32_bf16 v[126:129], v[188:191], v[182:185], v[126:129]
	v_mfma_f32_16x16x32_bf16 v[136:139], v[192:195], v[182:185], v[136:139]
	v_mfma_f32_16x16x32_bf16 v[140:143], v[208:211], v[182:185], v[140:143]
	v_mfma_f32_16x16x32_bf16 v[144:147], v[212:215], v[182:185], v[144:147]
	s_waitcnt vmcnt(0)
	s_barrier
	ds_read_b128 v[148:151], v78 offset:0
	ds_read_b128 v[152:155], v78 offset:2048
	ds_read_b128 v[156:159], v78 offset:4096
	ds_read_b128 v[160:163], v78 offset:6144
	ds_read_b128 v[188:191], v79 offset:49152
	ds_read_b128 v[192:195], v79 offset:51200
	ds_read_b128 v[208:211], v79 offset:53248
	ds_read_b128 v[212:215], v79 offset:55296
	ds_read_b128 v[164:167], v78 offset:16384
	ds_read_b128 v[168:171], v78 offset:18432
	ds_read_b128 v[174:177], v78 offset:20480
	ds_read_b128 v[182:185], v78 offset:22528
	s_setprio 1
	s_waitcnt lgkmcnt(4)
	v_mfma_f32_16x16x32_bf16 v[62:65], v[188:191], v[148:151], v[62:65]
	v_mfma_f32_16x16x32_bf16 v[58:61], v[192:195], v[148:151], v[58:61]
	v_mfma_f32_16x16x32_bf16 v[54:57], v[208:211], v[148:151], v[54:57]
	v_mfma_f32_16x16x32_bf16 v[50:53], v[212:215], v[148:151], v[50:53]
	v_mfma_f32_16x16x32_bf16 v[46:49], v[188:191], v[152:155], v[46:49]
	v_mfma_f32_16x16x32_bf16 v[42:45], v[192:195], v[152:155], v[42:45]
	v_mfma_f32_16x16x32_bf16 v[38:41], v[208:211], v[152:155], v[38:41]
	v_mfma_f32_16x16x32_bf16 v[34:37], v[212:215], v[152:155], v[34:37]
	v_mfma_f32_16x16x32_bf16 v[30:33], v[188:191], v[156:159], v[30:33]
	v_mfma_f32_16x16x32_bf16 v[26:29], v[192:195], v[156:159], v[26:29]
	v_mfma_f32_16x16x32_bf16 v[22:25], v[208:211], v[156:159], v[22:25]
	v_mfma_f32_16x16x32_bf16 v[18:21], v[212:215], v[156:159], v[18:21]
	v_mfma_f32_16x16x32_bf16 v[14:17], v[188:191], v[160:163], v[14:17]
	v_mfma_f32_16x16x32_bf16 v[10:13], v[192:195], v[160:163], v[10:13]
	v_mfma_f32_16x16x32_bf16 v[6:9], v[208:211], v[160:163], v[6:9]
	v_mfma_f32_16x16x32_bf16 v[2:5], v[212:215], v[160:163], v[2:5]
	s_waitcnt lgkmcnt(0)
	v_mfma_f32_16x16x32_bf16 v[66:69], v[188:191], v[164:167], v[66:69]
	v_mfma_f32_16x16x32_bf16 v[70:73], v[192:195], v[164:167], v[70:73]
	v_mfma_f32_16x16x32_bf16 v[82:85], v[208:211], v[164:167], v[82:85]
	v_mfma_f32_16x16x32_bf16 v[88:91], v[212:215], v[164:167], v[88:91]
	v_mfma_f32_16x16x32_bf16 v[92:95], v[188:191], v[168:171], v[92:95]
	v_mfma_f32_16x16x32_bf16 v[96:99], v[192:195], v[168:171], v[96:99]
	v_mfma_f32_16x16x32_bf16 v[100:103], v[208:211], v[168:171], v[100:103]
	v_mfma_f32_16x16x32_bf16 v[106:109], v[212:215], v[168:171], v[106:109]
	v_mfma_f32_16x16x32_bf16 v[110:113], v[188:191], v[174:177], v[110:113]
	v_mfma_f32_16x16x32_bf16 v[114:117], v[192:195], v[174:177], v[114:117]
	v_mfma_f32_16x16x32_bf16 v[118:121], v[208:211], v[174:177], v[118:121]
	v_mfma_f32_16x16x32_bf16 v[122:125], v[212:215], v[174:177], v[122:125]
	v_mfma_f32_16x16x32_bf16 v[126:129], v[188:191], v[182:185], v[126:129]
	v_mfma_f32_16x16x32_bf16 v[136:139], v[192:195], v[182:185], v[136:139]
	v_mfma_f32_16x16x32_bf16 v[140:143], v[208:211], v[182:185], v[140:143]
	v_mfma_f32_16x16x32_bf16 v[144:147], v[212:215], v[182:185], v[144:147]
	s_setprio 0
	ds_read_b128 v[148:151], v80 offset:0
	ds_read_b128 v[152:155], v80 offset:2048
	ds_read_b128 v[156:159], v80 offset:4096
	ds_read_b128 v[160:163], v80 offset:6144
	ds_read_b128 v[188:191], v81 offset:49152
	ds_read_b128 v[192:195], v81 offset:51200
	ds_read_b128 v[208:211], v81 offset:53248
	ds_read_b128 v[212:215], v81 offset:55296
	ds_read_b128 v[164:167], v80 offset:16384
	ds_read_b128 v[168:171], v80 offset:18432
	ds_read_b128 v[174:177], v80 offset:20480
	ds_read_b128 v[182:185], v80 offset:22528
	s_setprio 1
	s_waitcnt lgkmcnt(4)
	v_mfma_f32_16x16x32_bf16 v[62:65], v[188:191], v[148:151], v[62:65]
	v_mfma_f32_16x16x32_bf16 v[58:61], v[192:195], v[148:151], v[58:61]
	v_mfma_f32_16x16x32_bf16 v[54:57], v[208:211], v[148:151], v[54:57]
	v_mfma_f32_16x16x32_bf16 v[50:53], v[212:215], v[148:151], v[50:53]
	v_mfma_f32_16x16x32_bf16 v[46:49], v[188:191], v[152:155], v[46:49]
	v_mfma_f32_16x16x32_bf16 v[42:45], v[192:195], v[152:155], v[42:45]
	v_mfma_f32_16x16x32_bf16 v[38:41], v[208:211], v[152:155], v[38:41]
	v_mfma_f32_16x16x32_bf16 v[34:37], v[212:215], v[152:155], v[34:37]
	v_mfma_f32_16x16x32_bf16 v[30:33], v[188:191], v[156:159], v[30:33]
	v_mfma_f32_16x16x32_bf16 v[26:29], v[192:195], v[156:159], v[26:29]
	v_mfma_f32_16x16x32_bf16 v[22:25], v[208:211], v[156:159], v[22:25]
	v_mfma_f32_16x16x32_bf16 v[18:21], v[212:215], v[156:159], v[18:21]
	v_mfma_f32_16x16x32_bf16 v[14:17], v[188:191], v[160:163], v[14:17]
	v_mfma_f32_16x16x32_bf16 v[10:13], v[192:195], v[160:163], v[10:13]
	v_mfma_f32_16x16x32_bf16 v[6:9], v[208:211], v[160:163], v[6:9]
	v_mfma_f32_16x16x32_bf16 v[2:5], v[212:215], v[160:163], v[2:5]
	s_waitcnt lgkmcnt(0)
	v_mfma_f32_16x16x32_bf16 v[66:69], v[188:191], v[164:167], v[66:69]
	v_mfma_f32_16x16x32_bf16 v[70:73], v[192:195], v[164:167], v[70:73]
	v_mfma_f32_16x16x32_bf16 v[82:85], v[208:211], v[164:167], v[82:85]
	v_mfma_f32_16x16x32_bf16 v[88:91], v[212:215], v[164:167], v[88:91]
	v_mfma_f32_16x16x32_bf16 v[92:95], v[188:191], v[168:171], v[92:95]
	v_mfma_f32_16x16x32_bf16 v[96:99], v[192:195], v[168:171], v[96:99]
	v_mfma_f32_16x16x32_bf16 v[100:103], v[208:211], v[168:171], v[100:103]
	v_mfma_f32_16x16x32_bf16 v[106:109], v[212:215], v[168:171], v[106:109]
	v_mfma_f32_16x16x32_bf16 v[110:113], v[188:191], v[174:177], v[110:113]
	v_mfma_f32_16x16x32_bf16 v[114:117], v[192:195], v[174:177], v[114:117]
	v_mfma_f32_16x16x32_bf16 v[118:121], v[208:211], v[174:177], v[118:121]
	v_mfma_f32_16x16x32_bf16 v[122:125], v[212:215], v[174:177], v[122:125]
	v_mfma_f32_16x16x32_bf16 v[126:129], v[188:191], v[182:185], v[126:129]
	v_mfma_f32_16x16x32_bf16 v[136:139], v[192:195], v[182:185], v[136:139]
	v_mfma_f32_16x16x32_bf16 v[140:143], v[208:211], v[182:185], v[140:143]
	v_mfma_f32_16x16x32_bf16 v[144:147], v[212:215], v[182:185], v[144:147]
	s_setprio 0
	s_nop 7
	s_nop 7
	s_nop 7
	v_mov_b32_e32 v148, v66
	v_mov_b32_e32 v149, v67
	v_mov_b32_e32 v150, v68
	v_mov_b32_e32 v151, v69
	v_mov_b32_e32 v152, v70
	v_mov_b32_e32 v153, v71
	v_mov_b32_e32 v154, v72
	v_mov_b32_e32 v155, v73
	v_mov_b32_e32 v156, v82
	v_mov_b32_e32 v157, v83
	v_mov_b32_e32 v158, v84
	v_mov_b32_e32 v159, v85
	v_mov_b32_e32 v160, v88
	v_mov_b32_e32 v161, v89
	v_mov_b32_e32 v162, v90
	v_mov_b32_e32 v163, v91
	v_mov_b32_e32 v164, v92
	v_mov_b32_e32 v165, v93
	v_mov_b32_e32 v166, v94
	v_mov_b32_e32 v167, v95
	v_mov_b32_e32 v168, v96
	v_mov_b32_e32 v169, v97
	v_mov_b32_e32 v170, v98
	v_mov_b32_e32 v171, v99
	v_mov_b32_e32 v174, v100
	v_mov_b32_e32 v175, v101
	v_mov_b32_e32 v176, v102
	v_mov_b32_e32 v177, v103
	v_mov_b32_e32 v182, v106
	v_mov_b32_e32 v183, v107
	v_mov_b32_e32 v184, v108
	v_mov_b32_e32 v185, v109
	v_mov_b32_e32 v188, v110
	v_mov_b32_e32 v189, v111
	v_mov_b32_e32 v190, v112
	v_mov_b32_e32 v191, v113
	v_mov_b32_e32 v192, v114
	v_mov_b32_e32 v193, v115
	v_mov_b32_e32 v194, v116
	v_mov_b32_e32 v195, v117
	v_mov_b32_e32 v208, v118
	v_mov_b32_e32 v209, v119
	v_mov_b32_e32 v210, v120
	v_mov_b32_e32 v211, v121
	v_mov_b32_e32 v212, v122
	v_mov_b32_e32 v213, v123
	v_mov_b32_e32 v214, v124
	v_mov_b32_e32 v215, v125
	v_mov_b32_e32 v216, v126
	v_mov_b32_e32 v217, v127
	v_mov_b32_e32 v218, v128
	v_mov_b32_e32 v219, v129
	v_mov_b32_e32 v220, v136
	v_mov_b32_e32 v221, v137
	v_mov_b32_e32 v222, v138
	v_mov_b32_e32 v223, v139
	v_mov_b32_e32 v242, v140
	v_mov_b32_e32 v243, v141
	v_mov_b32_e32 v244, v142
	v_mov_b32_e32 v245, v143
	v_mov_b32_e32 v199, v144
	v_mov_b32_e32 v206, v145
	v_mov_b32_e32 v207, v146
	v_mov_b32_e32 v226, v147
	s_add_i32 s48, s48, 1
	s_mov_b32 s65, 0
	v_readlane_b32 s2, v249, 0
	s_nop 0
	s_and_b32 s3, s2, 7
	s_lshr_b32 s2, s2, 3
	s_cmp_lt_u32 s2, 40
	s_cselect_b32 s38, 7, 6
	s_cmp_lt_u32 s48, s38
	s_cbranch_scc0 .Lg2_c1_extra
	s_lshl_b32 s20, s48, 6
	s_add_i32 s20, s20, s2
	s_cmp_ge_u32 s20, 0xd4
	s_cselect_b32 s21, 1, 0
	s_mul_i32 s60, s21, 0xd4
	s_sub_i32 s20, s20, s60
	s_lshr_b32 s61, s20, 2
	s_and_b32 s20, s20, 3
	s_lshl_b32 s21, s21, 3
	s_add_i32 s20, s20, s21
	s_lshl_b32 s20, s20, 3
	s_add_i32 s60, s20, s3
	s_add_i32 s64, s60, 32
	s_branch .Lg2_c1_have

.Lf2_k:
	s_waitcnt vmcnt(0)
	s_barrier
	ds_read_b128 v[148:151], v80 offset:0
	ds_read_b128 v[152:155], v80 offset:2048
	ds_read_b128 v[156:159], v80 offset:4096
	ds_read_b128 v[160:163], v80 offset:6144
	ds_read_b128 v[188:191], v144 offset:32768
	ds_read_b128 v[192:195], v144 offset:34816
	ds_read_b128 v[208:211], v144 offset:36864
	ds_read_b128 v[212:215], v144 offset:38912
	ds_read_b128 v[164:167], v80 offset:16384
	ds_read_b128 v[168:171], v80 offset:18432
	ds_read_b128 v[174:177], v80 offset:20480
	ds_read_b128 v[182:185], v80 offset:22528
	s_add_i32 m0, s64, 0xc000
	s_nop 0
	global_load_lds_dwordx4 v76, s[58:59]
	s_add_i32 m0, s64, 0xd000
	s_nop 0
	global_load_lds_dwordx4 v77, s[58:59]
	s_add_i32 m0, s64, 0xe000
	s_nop 0
	global_load_lds_dwordx4 v78, s[58:59]
	s_add_i32 m0, s64, 0xf000
	s_nop 0
	global_load_lds_dwordx4 v79, s[58:59]
	s_add_u32 s58, s58, 0x80
	s_addc_u32 s59, s59, 0
	s_setprio 1
	s_waitcnt lgkmcnt(4)
	v_mfma_f32_16x16x32_bf16 v[62:65], v[188:191], v[148:151], v[62:65]
	v_mfma_f32_16x16x32_bf16 v[54:57], v[192:195], v[148:151], v[54:57]
	v_mfma_f32_16x16x32_bf16 v[58:61], v[208:211], v[148:151], v[58:61]
	v_mfma_f32_16x16x32_bf16 v[50:53], v[212:215], v[148:151], v[50:53]
	v_mfma_f32_16x16x32_bf16 v[46:49], v[188:191], v[152:155], v[46:49]
	v_mfma_f32_16x16x32_bf16 v[38:41], v[192:195], v[152:155], v[38:41]
	v_mfma_f32_16x16x32_bf16 v[42:45], v[208:211], v[152:155], v[42:45]
	v_mfma_f32_16x16x32_bf16 v[34:37], v[212:215], v[152:155], v[34:37]
	v_mfma_f32_16x16x32_bf16 v[30:33], v[188:191], v[156:159], v[30:33]
	v_mfma_f32_16x16x32_bf16 v[22:25], v[192:195], v[156:159], v[22:25]
	v_mfma_f32_16x16x32_bf16 v[26:29], v[208:211], v[156:159], v[26:29]
	v_mfma_f32_16x16x32_bf16 v[18:21], v[212:215], v[156:159], v[18:21]
	v_mfma_f32_16x16x32_bf16 v[14:17], v[188:191], v[160:163], v[14:17]
	v_mfma_f32_16x16x32_bf16 v[6:9], v[192:195], v[160:163], v[6:9]
	v_mfma_f32_16x16x32_bf16 v[10:13], v[208:211], v[160:163], v[10:13]
	v_mfma_f32_16x16x32_bf16 v[2:5], v[212:215], v[160:163], v[2:5]
	s_waitcnt lgkmcnt(0)
	v_mfma_f32_16x16x32_bf16 v[66:69], v[188:191], v[164:167], v[66:69]
	v_mfma_f32_16x16x32_bf16 v[70:73], v[192:195], v[164:167], v[70:73]
	v_mfma_f32_16x16x32_bf16 v[82:85], v[208:211], v[164:167], v[82:85]
	v_mfma_f32_16x16x32_bf16 v[86:89], v[212:215], v[164:167], v[86:89]
	v_mfma_f32_16x16x32_bf16 v[90:93], v[188:191], v[168:171], v[90:93]
	v_mfma_f32_16x16x32_bf16 v[94:97], v[192:195], v[168:171], v[94:97]
	v_mfma_f32_16x16x32_bf16 v[98:101], v[208:211], v[168:171], v[98:101]
	v_mfma_f32_16x16x32_bf16 v[102:105], v[212:215], v[168:171], v[102:105]
	v_mfma_f32_16x16x32_bf16 v[106:109], v[188:191], v[174:177], v[106:109]
	v_mfma_f32_16x16x32_bf16 v[110:113], v[192:195], v[174:177], v[110:113]
	v_mfma_f32_16x16x32_bf16 v[114:117], v[208:211], v[174:177], v[114:117]
	v_mfma_f32_16x16x32_bf16 v[118:121], v[212:215], v[174:177], v[118:121]
	v_mfma_f32_16x16x32_bf16 v[122:125], v[188:191], v[182:185], v[122:125]
	v_mfma_f32_16x16x32_bf16 v[126:129], v[192:195], v[182:185], v[126:129]
	v_mfma_f32_16x16x32_bf16 v[136:139], v[208:211], v[182:185], v[136:139]
	v_mfma_f32_16x16x32_bf16 v[140:143], v[212:215], v[182:185], v[140:143]
	s_setprio 0
	ds_read_b128 v[148:151], v81 offset:0
	ds_read_b128 v[152:155], v81 offset:2048
	ds_read_b128 v[156:159], v81 offset:4096
	ds_read_b128 v[160:163], v81 offset:6144
	ds_read_b128 v[188:191], v145 offset:32768
	ds_read_b128 v[192:195], v145 offset:34816
	ds_read_b128 v[208:211], v145 offset:36864
	ds_read_b128 v[212:215], v145 offset:38912
	ds_read_b128 v[164:167], v81 offset:16384
	ds_read_b128 v[168:171], v81 offset:18432
	ds_read_b128 v[174:177], v81 offset:20480
	ds_read_b128 v[182:185], v81 offset:22528
	s_waitcnt lgkmcnt(0)
	s_barrier
	v_mfma_f32_16x16x32_bf16 v[62:65], v[188:191], v[148:151], v[62:65]
	s_add_i32 m0, s64, 0x0
	s_nop 0
	global_load_lds_dwordx4 v76, s[50:51]
	v_mfma_f32_16x16x32_bf16 v[54:57], v[192:195], v[148:151], v[54:57]
	s_add_i32 m0, s64, 0x1000
	s_nop 0
	global_load_lds_dwordx4 v77, s[50:51]
	v_mfma_f32_16x16x32_bf16 v[58:61], v[208:211], v[148:151], v[58:61]
	s_add_i32 m0, s64, 0x2000
	s_nop 0
	global_load_lds_dwordx4 v78, s[50:51]
	v_mfma_f32_16x16x32_bf16 v[50:53], v[212:215], v[148:151], v[50:53]
	s_add_i32 m0, s64, 0x3000
	s_nop 0
	global_load_lds_dwordx4 v79, s[50:51]
	v_mfma_f32_16x16x32_bf16 v[46:49], v[188:191], v[152:155], v[46:49]
	s_add_i32 m0, s64, 0x4000
	s_nop 0
	global_load_lds_dwordx4 v76, s[52:53]
	v_mfma_f32_16x16x32_bf16 v[38:41], v[192:195], v[152:155], v[38:41]
	s_add_i32 m0, s64, 0x5000
	s_nop 0
	global_load_lds_dwordx4 v77, s[52:53]
	v_mfma_f32_16x16x32_bf16 v[42:45], v[208:211], v[152:155], v[42:45]
	s_add_i32 m0, s64, 0x6000
	s_nop 0
	global_load_lds_dwordx4 v78, s[52:53]
	v_mfma_f32_16x16x32_bf16 v[34:37], v[212:215], v[152:155], v[34:37]
	s_add_i32 m0, s64, 0x7000
	s_nop 0
	global_load_lds_dwordx4 v79, s[52:53]
	v_mfma_f32_16x16x32_bf16 v[30:33], v[188:191], v[156:159], v[30:33]
	s_add_u32 s50, s50, 0x80
	s_addc_u32 s51, s51, 0
	v_mfma_f32_16x16x32_bf16 v[22:25], v[192:195], v[156:159], v[22:25]
	s_add_u32 s52, s52, 0x80
	s_addc_u32 s53, s53, 0
	v_mfma_f32_16x16x32_bf16 v[26:29], v[208:211], v[156:159], v[26:29]
	v_mfma_f32_16x16x32_bf16 v[18:21], v[212:215], v[156:159], v[18:21]
	v_mfma_f32_16x16x32_bf16 v[14:17], v[188:191], v[160:163], v[14:17]
	v_mfma_f32_16x16x32_bf16 v[6:9], v[192:195], v[160:163], v[6:9]
	v_mfma_f32_16x16x32_bf16 v[10:13], v[208:211], v[160:163], v[10:13]
	v_mfma_f32_16x16x32_bf16 v[2:5], v[212:215], v[160:163], v[2:5]
	v_mfma_f32_16x16x32_bf16 v[66:69], v[188:191], v[164:167], v[66:69]
	v_mfma_f32_16x16x32_bf16 v[70:73], v[192:195], v[164:167], v[70:73]
	v_mfma_f32_16x16x32_bf16 v[82:85], v[208:211], v[164:167], v[82:85]
	v_mfma_f32_16x16x32_bf16 v[86:89], v[212:215], v[164:167], v[86:89]
	v_mfma_f32_16x16x32_bf16 v[90:93], v[188:191], v[168:171], v[90:93]
	v_mfma_f32_16x16x32_bf16 v[94:97], v[192:195], v[168:171], v[94:97]
	v_mfma_f32_16x16x32_bf16 v[98:101], v[208:211], v[168:171], v[98:101]
	v_mfma_f32_16x16x32_bf16 v[102:105], v[212:215], v[168:171], v[102:105]
	v_mfma_f32_16x16x32_bf16 v[106:109], v[188:191], v[174:177], v[106:109]
	v_mfma_f32_16x16x32_bf16 v[110:113], v[192:195], v[174:177], v[110:113]
	v_mfma_f32_16x16x32_bf16 v[114:117], v[208:211], v[174:177], v[114:117]
	v_mfma_f32_16x16x32_bf16 v[118:121], v[212:215], v[174:177], v[118:121]
	v_mfma_f32_16x16x32_bf16 v[122:125], v[188:191], v[182:185], v[122:125]
	v_mfma_f32_16x16x32_bf16 v[126:129], v[192:195], v[182:185], v[126:129]
	v_mfma_f32_16x16x32_bf16 v[136:139], v[208:211], v[182:185], v[136:139]
	v_mfma_f32_16x16x32_bf16 v[140:143], v[212:215], v[182:185], v[140:143]
	s_waitcnt vmcnt(0)
	s_barrier
	ds_read_b128 v[148:151], v80 offset:0
	ds_read_b128 v[152:155], v80 offset:2048
	ds_read_b128 v[156:159], v80 offset:4096
	ds_read_b128 v[160:163], v80 offset:6144
	ds_read_b128 v[188:191], v144 offset:49152
	ds_read_b128 v[192:195], v144 offset:51200
	ds_read_b128 v[208:211], v144 offset:53248
	ds_read_b128 v[212:215], v144 offset:55296
	ds_read_b128 v[164:167], v80 offset:16384
	ds_read_b128 v[168:171], v80 offset:18432
	ds_read_b128 v[174:177], v80 offset:20480
	ds_read_b128 v[182:185], v80 offset:22528
	s_add_i32 m0, s64, 0x8000
	s_nop 0
	global_load_lds_dwordx4 v76, s[58:59]
	s_add_i32 m0, s64, 0x9000
	s_nop 0
	global_load_lds_dwordx4 v77, s[58:59]
	s_add_i32 m0, s64, 0xa000
	s_nop 0
	global_load_lds_dwordx4 v78, s[58:59]
	s_add_i32 m0, s64, 0xb000
	s_nop 0
	global_load_lds_dwordx4 v79, s[58:59]
	s_add_u32 s58, s58, 0x80
	s_addc_u32 s59, s59, 0
	s_setprio 1
	s_waitcnt lgkmcnt(4)
	v_mfma_f32_16x16x32_bf16 v[62:65], v[188:191], v[148:151], v[62:65]
	v_mfma_f32_16x16x32_bf16 v[54:57], v[192:195], v[148:151], v[54:57]
	v_mfma_f32_16x16x32_bf16 v[58:61], v[208:211], v[148:151], v[58:61]
	v_mfma_f32_16x16x32_bf16 v[50:53], v[212:215], v[148:151], v[50:53]
	v_mfma_f32_16x16x32_bf16 v[46:49], v[188:191], v[152:155], v[46:49]
	v_mfma_f32_16x16x32_bf16 v[38:41], v[192:195], v[152:155], v[38:41]
	v_mfma_f32_16x16x32_bf16 v[42:45], v[208:211], v[152:155], v[42:45]
	v_mfma_f32_16x16x32_bf16 v[34:37], v[212:215], v[152:155], v[34:37]
	v_mfma_f32_16x16x32_bf16 v[30:33], v[188:191], v[156:159], v[30:33]
	v_mfma_f32_16x16x32_bf16 v[22:25], v[192:195], v[156:159], v[22:25]
	v_mfma_f32_16x16x32_bf16 v[26:29], v[208:211], v[156:159], v[26:29]
	v_mfma_f32_16x16x32_bf16 v[18:21], v[212:215], v[156:159], v[18:21]
	v_mfma_f32_16x16x32_bf16 v[14:17], v[188:191], v[160:163], v[14:17]
	v_mfma_f32_16x16x32_bf16 v[6:9], v[192:195], v[160:163], v[6:9]
	v_mfma_f32_16x16x32_bf16 v[10:13], v[208:211], v[160:163], v[10:13]
	v_mfma_f32_16x16x32_bf16 v[2:5], v[212:215], v[160:163], v[2:5]
	s_waitcnt lgkmcnt(0)
	v_mfma_f32_16x16x32_bf16 v[66:69], v[188:191], v[164:167], v[66:69]
	v_mfma_f32_16x16x32_bf16 v[70:73], v[192:195], v[164:167], v[70:73]
	v_mfma_f32_16x16x32_bf16 v[82:85], v[208:211], v[164:167], v[82:85]
	v_mfma_f32_16x16x32_bf16 v[86:89], v[212:215], v[164:167], v[86:89]
	v_mfma_f32_16x16x32_bf16 v[90:93], v[188:191], v[168:171], v[90:93]
	v_mfma_f32_16x16x32_bf16 v[94:97], v[192:195], v[168:171], v[94:97]
	v_mfma_f32_16x16x32_bf16 v[98:101], v[208:211], v[168:171], v[98:101]
	v_mfma_f32_16x16x32_bf16 v[102:105], v[212:215], v[168:171], v[102:105]
	v_mfma_f32_16x16x32_bf16 v[106:109], v[188:191], v[174:177], v[106:109]
	v_mfma_f32_16x16x32_bf16 v[110:113], v[192:195], v[174:177], v[110:113]
	v_mfma_f32_16x16x32_bf16 v[114:117], v[208:211], v[174:177], v[114:117]
	v_mfma_f32_16x16x32_bf16 v[118:121], v[212:215], v[174:177], v[118:121]
	v_mfma_f32_16x16x32_bf16 v[122:125], v[188:191], v[182:185], v[122:125]
	v_mfma_f32_16x16x32_bf16 v[126:129], v[192:195], v[182:185], v[126:129]
	v_mfma_f32_16x16x32_bf16 v[136:139], v[208:211], v[182:185], v[136:139]
	v_mfma_f32_16x16x32_bf16 v[140:143], v[212:215], v[182:185], v[140:143]
	s_setprio 0
	ds_read_b128 v[148:151], v81 offset:0
	ds_read_b128 v[152:155], v81 offset:2048
	ds_read_b128 v[156:159], v81 offset:4096
	ds_read_b128 v[160:163], v81 offset:6144
	ds_read_b128 v[188:191], v145 offset:49152
	ds_read_b128 v[192:195], v145 offset:51200
	ds_read_b128 v[208:211], v145 offset:53248
	ds_read_b128 v[212:215], v145 offset:55296
	ds_read_b128 v[164:167], v81 offset:16384
	ds_read_b128 v[168:171], v81 offset:18432
	ds_read_b128 v[174:177], v81 offset:20480
	ds_read_b128 v[182:185], v81 offset:22528
	s_waitcnt lgkmcnt(0)
	s_barrier
	v_mfma_f32_16x16x32_bf16 v[62:65], v[188:191], v[148:151], v[62:65]
	s_add_i32 m0, s64, 0x0
	s_nop 0
	global_load_lds_dwordx4 v76, s[50:51]
	v_mfma_f32_16x16x32_bf16 v[54:57], v[192:195], v[148:151], v[54:57]
	s_add_i32 m0, s64, 0x1000
	s_nop 0
	global_load_lds_dwordx4 v77, s[50:51]
	v_mfma_f32_16x16x32_bf16 v[58:61], v[208:211], v[148:151], v[58:61]
	s_add_i32 m0, s64, 0x2000
	s_nop 0
	global_load_lds_dwordx4 v78, s[50:51]
	v_mfma_f32_16x16x32_bf16 v[50:53], v[212:215], v[148:151], v[50:53]
	s_add_i32 m0, s64, 0x3000
	s_nop 0
	global_load_lds_dwordx4 v79, s[50:51]
	v_mfma_f32_16x16x32_bf16 v[46:49], v[188:191], v[152:155], v[46:49]
	s_add_i32 m0, s64, 0x4000
	s_nop 0
	global_load_lds_dwordx4 v76, s[52:53]
	v_mfma_f32_16x16x32_bf16 v[38:41], v[192:195], v[152:155], v[38:41]
	s_add_i32 m0, s64, 0x5000
	s_nop 0
	global_load_lds_dwordx4 v77, s[52:53]
	v_mfma_f32_16x16x32_bf16 v[42:45], v[208:211], v[152:155], v[42:45]
	s_add_i32 m0, s64, 0x6000
	s_nop 0
	global_load_lds_dwordx4 v78, s[52:53]
	v_mfma_f32_16x16x32_bf16 v[34:37], v[212:215], v[152:155], v[34:37]
	s_add_i32 m0, s64, 0x7000
	s_nop 0
	global_load_lds_dwordx4 v79, s[52:53]
	v_mfma_f32_16x16x32_bf16 v[30:33], v[188:191], v[156:159], v[30:33]
	s_add_u32 s50, s50, 0x80
	s_addc_u32 s51, s51, 0
	v_mfma_f32_16x16x32_bf16 v[22:25], v[192:195], v[156:159], v[22:25]
	s_add_u32 s52, s52, 0x80
	s_addc_u32 s53, s53, 0
	v_mfma_f32_16x16x32_bf16 v[26:29], v[208:211], v[156:159], v[26:29]
	v_mfma_f32_16x16x32_bf16 v[18:21], v[212:215], v[156:159], v[18:21]
	v_mfma_f32_16x16x32_bf16 v[14:17], v[188:191], v[160:163], v[14:17]
	v_mfma_f32_16x16x32_bf16 v[6:9], v[192:195], v[160:163], v[6:9]
	v_mfma_f32_16x16x32_bf16 v[10:13], v[208:211], v[160:163], v[10:13]
	v_mfma_f32_16x16x32_bf16 v[2:5], v[212:215], v[160:163], v[2:5]
	v_mfma_f32_16x16x32_bf16 v[66:69], v[188:191], v[164:167], v[66:69]
	v_mfma_f32_16x16x32_bf16 v[70:73], v[192:195], v[164:167], v[70:73]
	v_mfma_f32_16x16x32_bf16 v[82:85], v[208:211], v[164:167], v[82:85]
	v_mfma_f32_16x16x32_bf16 v[86:89], v[212:215], v[164:167], v[86:89]
	v_mfma_f32_16x16x32_bf16 v[90:93], v[188:191], v[168:171], v[90:93]
	v_mfma_f32_16x16x32_bf16 v[94:97], v[192:195], v[168:171], v[94:97]
	v_mfma_f32_16x16x32_bf16 v[98:101], v[208:211], v[168:171], v[98:101]
	v_mfma_f32_16x16x32_bf16 v[102:105], v[212:215], v[168:171], v[102:105]
	v_mfma_f32_16x16x32_bf16 v[106:109], v[188:191], v[174:177], v[106:109]
	v_mfma_f32_16x16x32_bf16 v[110:113], v[192:195], v[174:177], v[110:113]
	v_mfma_f32_16x16x32_bf16 v[114:117], v[208:211], v[174:177], v[114:117]
	v_mfma_f32_16x16x32_bf16 v[118:121], v[212:215], v[174:177], v[118:121]
	v_mfma_f32_16x16x32_bf16 v[122:125], v[188:191], v[182:185], v[122:125]
	v_mfma_f32_16x16x32_bf16 v[126:129], v[192:195], v[182:185], v[126:129]
	v_mfma_f32_16x16x32_bf16 v[136:139], v[208:211], v[182:185], v[136:139]
	v_mfma_f32_16x16x32_bf16 v[140:143], v[212:215], v[182:185], v[140:143]
	s_add_i32 s65, s65, -1
	s_cmp_lg_u32 s65, 0
	s_cbranch_scc1 .Lf2_k
	s_waitcnt vmcnt(0)
	s_barrier
	ds_read_b128 v[148:151], v80 offset:0
	ds_read_b128 v[152:155], v80 offset:2048
	ds_read_b128 v[156:159], v80 offset:4096
	ds_read_b128 v[160:163], v80 offset:6144
	ds_read_b128 v[188:191], v144 offset:32768
	ds_read_b128 v[192:195], v144 offset:34816
	ds_read_b128 v[208:211], v144 offset:36864
	ds_read_b128 v[212:215], v144 offset:38912
	ds_read_b128 v[164:167], v80 offset:16384
	ds_read_b128 v[168:171], v80 offset:18432
	ds_read_b128 v[174:177], v80 offset:20480
	ds_read_b128 v[182:185], v80 offset:22528
	s_add_i32 m0, s64, 0xc000
	s_nop 0
	global_load_lds_dwordx4 v76, s[58:59]
	s_add_i32 m0, s64, 0xd000
	s_nop 0
	global_load_lds_dwordx4 v77, s[58:59]
	s_add_i32 m0, s64, 0xe000
	s_nop 0
	global_load_lds_dwordx4 v78, s[58:59]
	s_add_i32 m0, s64, 0xf000
	s_nop 0
	global_load_lds_dwordx4 v79, s[58:59]
	s_add_u32 s58, s58, 0x80
	s_addc_u32 s59, s59, 0
	s_setprio 1
	s_waitcnt lgkmcnt(4)
	v_mfma_f32_16x16x32_bf16 v[62:65], v[188:191], v[148:151], v[62:65]
	v_mfma_f32_16x16x32_bf16 v[54:57], v[192:195], v[148:151], v[54:57]
	v_mfma_f32_16x16x32_bf16 v[58:61], v[208:211], v[148:151], v[58:61]
	v_mfma_f32_16x16x32_bf16 v[50:53], v[212:215], v[148:151], v[50:53]
	v_mfma_f32_16x16x32_bf16 v[46:49], v[188:191], v[152:155], v[46:49]
	v_mfma_f32_16x16x32_bf16 v[38:41], v[192:195], v[152:155], v[38:41]
	v_mfma_f32_16x16x32_bf16 v[42:45], v[208:211], v[152:155], v[42:45]
	v_mfma_f32_16x16x32_bf16 v[34:37], v[212:215], v[152:155], v[34:37]
	v_mfma_f32_16x16x32_bf16 v[30:33], v[188:191], v[156:159], v[30:33]
	v_mfma_f32_16x16x32_bf16 v[22:25], v[192:195], v[156:159], v[22:25]
	v_mfma_f32_16x16x32_bf16 v[26:29], v[208:211], v[156:159], v[26:29]
	v_mfma_f32_16x16x32_bf16 v[18:21], v[212:215], v[156:159], v[18:21]
	v_mfma_f32_16x16x32_bf16 v[14:17], v[188:191], v[160:163], v[14:17]
	v_mfma_f32_16x16x32_bf16 v[6:9], v[192:195], v[160:163], v[6:9]
	v_mfma_f32_16x16x32_bf16 v[10:13], v[208:211], v[160:163], v[10:13]
	v_mfma_f32_16x16x32_bf16 v[2:5], v[212:215], v[160:163], v[2:5]
	s_waitcnt lgkmcnt(0)
	v_mfma_f32_16x16x32_bf16 v[66:69], v[188:191], v[164:167], v[66:69]
	v_mfma_f32_16x16x32_bf16 v[70:73], v[192:195], v[164:167], v[70:73]
	v_mfma_f32_16x16x32_bf16 v[82:85], v[208:211], v[164:167], v[82:85]
	v_mfma_f32_16x16x32_bf16 v[86:89], v[212:215], v[164:167], v[86:89]
	v_mfma_f32_16x16x32_bf16 v[90:93], v[188:191], v[168:171], v[90:93]
	v_mfma_f32_16x16x32_bf16 v[94:97], v[192:195], v[168:171], v[94:97]
	v_mfma_f32_16x16x32_bf16 v[98:101], v[208:211], v[168:171], v[98:101]
	v_mfma_f32_16x16x32_bf16 v[102:105], v[212:215], v[168:171], v[102:105]
	v_mfma_f32_16x16x32_bf16 v[106:109], v[188:191], v[174:177], v[106:109]
	v_mfma_f32_16x16x32_bf16 v[110:113], v[192:195], v[174:177], v[110:113]
	v_mfma_f32_16x16x32_bf16 v[114:117], v[208:211], v[174:177], v[114:117]
	v_mfma_f32_16x16x32_bf16 v[118:121], v[212:215], v[174:177], v[118:121]
	v_mfma_f32_16x16x32_bf16 v[122:125], v[188:191], v[182:185], v[122:125]
	v_mfma_f32_16x16x32_bf16 v[126:129], v[192:195], v[182:185], v[126:129]
	v_mfma_f32_16x16x32_bf16 v[136:139], v[208:211], v[182:185], v[136:139]
	v_mfma_f32_16x16x32_bf16 v[140:143], v[212:215], v[182:185], v[140:143]
	s_setprio 0
	ds_read_b128 v[148:151], v81 offset:0
	ds_read_b128 v[152:155], v81 offset:2048
	ds_read_b128 v[156:159], v81 offset:4096
	ds_read_b128 v[160:163], v81 offset:6144
	ds_read_b128 v[188:191], v145 offset:32768
	ds_read_b128 v[192:195], v145 offset:34816
	ds_read_b128 v[208:211], v145 offset:36864
	ds_read_b128 v[212:215], v145 offset:38912
	ds_read_b128 v[164:167], v81 offset:16384
	ds_read_b128 v[168:171], v81 offset:18432
	ds_read_b128 v[174:177], v81 offset:20480
	ds_read_b128 v[182:185], v81 offset:22528
	s_waitcnt lgkmcnt(0)
	s_barrier
	v_mfma_f32_16x16x32_bf16 v[62:65], v[188:191], v[148:151], v[62:65]
	s_add_i32 m0, s64, 0x0
	s_nop 0
	global_load_lds_dwordx4 v76, s[50:51]
	v_mfma_f32_16x16x32_bf16 v[54:57], v[192:195], v[148:151], v[54:57]
	s_add_i32 m0, s64, 0x1000
	s_nop 0
	global_load_lds_dwordx4 v77, s[50:51]
	v_mfma_f32_16x16x32_bf16 v[58:61], v[208:211], v[148:151], v[58:61]
	s_add_i32 m0, s64, 0x2000
	s_nop 0
	global_load_lds_dwordx4 v78, s[50:51]
	v_mfma_f32_16x16x32_bf16 v[50:53], v[212:215], v[148:151], v[50:53]
	s_add_i32 m0, s64, 0x3000
	s_nop 0
	global_load_lds_dwordx4 v79, s[50:51]
	v_mfma_f32_16x16x32_bf16 v[46:49], v[188:191], v[152:155], v[46:49]
	s_add_i32 m0, s64, 0x4000
	s_nop 0
	global_load_lds_dwordx4 v76, s[52:53]
	v_mfma_f32_16x16x32_bf16 v[38:41], v[192:195], v[152:155], v[38:41]
	s_add_i32 m0, s64, 0x5000
	s_nop 0
	global_load_lds_dwordx4 v77, s[52:53]
	v_mfma_f32_16x16x32_bf16 v[42:45], v[208:211], v[152:155], v[42:45]
	s_add_i32 m0, s64, 0x6000
	s_nop 0
	global_load_lds_dwordx4 v78, s[52:53]
	v_mfma_f32_16x16x32_bf16 v[34:37], v[212:215], v[152:155], v[34:37]
	s_add_i32 m0, s64, 0x7000
	s_nop 0
	global_load_lds_dwordx4 v79, s[52:53]
	v_mfma_f32_16x16x32_bf16 v[30:33], v[188:191], v[156:159], v[30:33]
	s_add_u32 s50, s50, 0x80
	s_addc_u32 s51, s51, 0
	v_mfma_f32_16x16x32_bf16 v[22:25], v[192:195], v[156:159], v[22:25]
	s_add_u32 s52, s52, 0x80
	s_addc_u32 s53, s53, 0
	v_mfma_f32_16x16x32_bf16 v[26:29], v[208:211], v[156:159], v[26:29]
	v_mfma_f32_16x16x32_bf16 v[18:21], v[212:215], v[156:159], v[18:21]
	v_mfma_f32_16x16x32_bf16 v[14:17], v[188:191], v[160:163], v[14:17]
	v_mfma_f32_16x16x32_bf16 v[6:9], v[192:195], v[160:163], v[6:9]
	v_mfma_f32_16x16x32_bf16 v[10:13], v[208:211], v[160:163], v[10:13]
	v_mfma_f32_16x16x32_bf16 v[2:5], v[212:215], v[160:163], v[2:5]
	v_mfma_f32_16x16x32_bf16 v[66:69], v[188:191], v[164:167], v[66:69]
	v_mfma_f32_16x16x32_bf16 v[70:73], v[192:195], v[164:167], v[70:73]
	v_mfma_f32_16x16x32_bf16 v[82:85], v[208:211], v[164:167], v[82:85]
	v_mfma_f32_16x16x32_bf16 v[86:89], v[212:215], v[164:167], v[86:89]
	v_mfma_f32_16x16x32_bf16 v[90:93], v[188:191], v[168:171], v[90:93]
	v_mfma_f32_16x16x32_bf16 v[94:97], v[192:195], v[168:171], v[94:97]
	v_mfma_f32_16x16x32_bf16 v[98:101], v[208:211], v[168:171], v[98:101]
	v_mfma_f32_16x16x32_bf16 v[102:105], v[212:215], v[168:171], v[102:105]
	v_mfma_f32_16x16x32_bf16 v[106:109], v[188:191], v[174:177], v[106:109]
	v_mfma_f32_16x16x32_bf16 v[110:113], v[192:195], v[174:177], v[110:113]
	v_mfma_f32_16x16x32_bf16 v[114:117], v[208:211], v[174:177], v[114:117]
	v_mfma_f32_16x16x32_bf16 v[118:121], v[212:215], v[174:177], v[118:121]
	v_mfma_f32_16x16x32_bf16 v[122:125], v[188:191], v[182:185], v[122:125]
	v_mfma_f32_16x16x32_bf16 v[126:129], v[192:195], v[182:185], v[126:129]
	v_mfma_f32_16x16x32_bf16 v[136:139], v[208:211], v[182:185], v[136:139]
	v_mfma_f32_16x16x32_bf16 v[140:143], v[212:215], v[182:185], v[140:143]
	s_waitcnt vmcnt(0)
	s_barrier
	ds_read_b128 v[148:151], v80 offset:0
	ds_read_b128 v[152:155], v80 offset:2048
	ds_read_b128 v[156:159], v80 offset:4096
	ds_read_b128 v[160:163], v80 offset:6144
	ds_read_b128 v[188:191], v144 offset:49152
	ds_read_b128 v[192:195], v144 offset:51200
	ds_read_b128 v[208:211], v144 offset:53248
	ds_read_b128 v[212:215], v144 offset:55296
	ds_read_b128 v[164:167], v80 offset:16384
	ds_read_b128 v[168:171], v80 offset:18432
	ds_read_b128 v[174:177], v80 offset:20480
	ds_read_b128 v[182:185], v80 offset:22528
	s_setprio 1
	s_waitcnt lgkmcnt(4)
	v_mfma_f32_16x16x32_bf16 v[62:65], v[188:191], v[148:151], v[62:65]
	v_mfma_f32_16x16x32_bf16 v[54:57], v[192:195], v[148:151], v[54:57]
	v_mfma_f32_16x16x32_bf16 v[58:61], v[208:211], v[148:151], v[58:61]
	v_mfma_f32_16x16x32_bf16 v[50:53], v[212:215], v[148:151], v[50:53]
	v_mfma_f32_16x16x32_bf16 v[46:49], v[188:191], v[152:155], v[46:49]
	v_mfma_f32_16x16x32_bf16 v[38:41], v[192:195], v[152:155], v[38:41]
	v_mfma_f32_16x16x32_bf16 v[42:45], v[208:211], v[152:155], v[42:45]
	v_mfma_f32_16x16x32_bf16 v[34:37], v[212:215], v[152:155], v[34:37]
	v_mfma_f32_16x16x32_bf16 v[30:33], v[188:191], v[156:159], v[30:33]
	v_mfma_f32_16x16x32_bf16 v[22:25], v[192:195], v[156:159], v[22:25]
	v_mfma_f32_16x16x32_bf16 v[26:29], v[208:211], v[156:159], v[26:29]
	v_mfma_f32_16x16x32_bf16 v[18:21], v[212:215], v[156:159], v[18:21]
	v_mfma_f32_16x16x32_bf16 v[14:17], v[188:191], v[160:163], v[14:17]
	v_mfma_f32_16x16x32_bf16 v[6:9], v[192:195], v[160:163], v[6:9]
	v_mfma_f32_16x16x32_bf16 v[10:13], v[208:211], v[160:163], v[10:13]
	v_mfma_f32_16x16x32_bf16 v[2:5], v[212:215], v[160:163], v[2:5]
	s_waitcnt lgkmcnt(0)
	v_mfma_f32_16x16x32_bf16 v[66:69], v[188:191], v[164:167], v[66:69]
	v_mfma_f32_16x16x32_bf16 v[70:73], v[192:195], v[164:167], v[70:73]
	v_mfma_f32_16x16x32_bf16 v[82:85], v[208:211], v[164:167], v[82:85]
	v_mfma_f32_16x16x32_bf16 v[86:89], v[212:215], v[164:167], v[86:89]
	v_mfma_f32_16x16x32_bf16 v[90:93], v[188:191], v[168:171], v[90:93]
	v_mfma_f32_16x16x32_bf16 v[94:97], v[192:195], v[168:171], v[94:97]
	v_mfma_f32_16x16x32_bf16 v[98:101], v[208:211], v[168:171], v[98:101]
	v_mfma_f32_16x16x32_bf16 v[102:105], v[212:215], v[168:171], v[102:105]
	v_mfma_f32_16x16x32_bf16 v[106:109], v[188:191], v[174:177], v[106:109]
	v_mfma_f32_16x16x32_bf16 v[110:113], v[192:195], v[174:177], v[110:113]
	v_mfma_f32_16x16x32_bf16 v[114:117], v[208:211], v[174:177], v[114:117]
	v_mfma_f32_16x16x32_bf16 v[118:121], v[212:215], v[174:177], v[118:121]
	v_mfma_f32_16x16x32_bf16 v[122:125], v[188:191], v[182:185], v[122:125]
	v_mfma_f32_16x16x32_bf16 v[126:129], v[192:195], v[182:185], v[126:129]
	v_mfma_f32_16x16x32_bf16 v[136:139], v[208:211], v[182:185], v[136:139]
	v_mfma_f32_16x16x32_bf16 v[140:143], v[212:215], v[182:185], v[140:143]
	s_setprio 0
	ds_read_b128 v[148:151], v81 offset:0
	ds_read_b128 v[152:155], v81 offset:2048
	ds_read_b128 v[156:159], v81 offset:4096
	ds_read_b128 v[160:163], v81 offset:6144
	ds_read_b128 v[188:191], v145 offset:49152
	ds_read_b128 v[192:195], v145 offset:51200
	ds_read_b128 v[208:211], v145 offset:53248
	ds_read_b128 v[212:215], v145 offset:55296
	ds_read_b128 v[164:167], v81 offset:16384
	ds_read_b128 v[168:171], v81 offset:18432
	ds_read_b128 v[174:177], v81 offset:20480
	ds_read_b128 v[182:185], v81 offset:22528
	s_setprio 1
	s_waitcnt lgkmcnt(4)
	v_mfma_f32_16x16x32_bf16 v[62:65], v[188:191], v[148:151], v[62:65]
	v_mfma_f32_16x16x32_bf16 v[54:57], v[192:195], v[148:151], v[54:57]
	v_mfma_f32_16x16x32_bf16 v[58:61], v[208:211], v[148:151], v[58:61]
	v_mfma_f32_16x16x32_bf16 v[50:53], v[212:215], v[148:151], v[50:53]
	v_mfma_f32_16x16x32_bf16 v[46:49], v[188:191], v[152:155], v[46:49]
	v_mfma_f32_16x16x32_bf16 v[38:41], v[192:195], v[152:155], v[38:41]
	v_mfma_f32_16x16x32_bf16 v[42:45], v[208:211], v[152:155], v[42:45]
	v_mfma_f32_16x16x32_bf16 v[34:37], v[212:215], v[152:155], v[34:37]
	v_mfma_f32_16x16x32_bf16 v[30:33], v[188:191], v[156:159], v[30:33]
	v_mfma_f32_16x16x32_bf16 v[22:25], v[192:195], v[156:159], v[22:25]
	v_mfma_f32_16x16x32_bf16 v[26:29], v[208:211], v[156:159], v[26:29]
	v_mfma_f32_16x16x32_bf16 v[18:21], v[212:215], v[156:159], v[18:21]
	v_mfma_f32_16x16x32_bf16 v[14:17], v[188:191], v[160:163], v[14:17]
	v_mfma_f32_16x16x32_bf16 v[6:9], v[192:195], v[160:163], v[6:9]
	v_mfma_f32_16x16x32_bf16 v[10:13], v[208:211], v[160:163], v[10:13]
	v_mfma_f32_16x16x32_bf16 v[2:5], v[212:215], v[160:163], v[2:5]
	s_waitcnt lgkmcnt(0)
	v_mfma_f32_16x16x32_bf16 v[66:69], v[188:191], v[164:167], v[66:69]
	v_mfma_f32_16x16x32_bf16 v[70:73], v[192:195], v[164:167], v[70:73]
	v_mfma_f32_16x16x32_bf16 v[82:85], v[208:211], v[164:167], v[82:85]
	v_mfma_f32_16x16x32_bf16 v[86:89], v[212:215], v[164:167], v[86:89]
	v_mfma_f32_16x16x32_bf16 v[90:93], v[188:191], v[168:171], v[90:93]
	v_mfma_f32_16x16x32_bf16 v[94:97], v[192:195], v[168:171], v[94:97]
	v_mfma_f32_16x16x32_bf16 v[98:101], v[208:211], v[168:171], v[98:101]
	v_mfma_f32_16x16x32_bf16 v[102:105], v[212:215], v[168:171], v[102:105]
	v_mfma_f32_16x16x32_bf16 v[106:109], v[188:191], v[174:177], v[106:109]
	v_mfma_f32_16x16x32_bf16 v[110:113], v[192:195], v[174:177], v[110:113]
	v_mfma_f32_16x16x32_bf16 v[114:117], v[208:211], v[174:177], v[114:117]
	v_mfma_f32_16x16x32_bf16 v[118:121], v[212:215], v[174:177], v[118:121]
	v_mfma_f32_16x16x32_bf16 v[122:125], v[188:191], v[182:185], v[122:125]
	v_mfma_f32_16x16x32_bf16 v[126:129], v[192:195], v[182:185], v[126:129]
	v_mfma_f32_16x16x32_bf16 v[136:139], v[208:211], v[182:185], v[136:139]
	v_mfma_f32_16x16x32_bf16 v[140:143], v[212:215], v[182:185], v[140:143]
	s_setprio 0
	s_nop 7
	s_nop 7
	s_nop 7
	v_mov_b32_e32 v148, v66
	v_mov_b32_e32 v149, v67
	v_mov_b32_e32 v150, v68
	v_mov_b32_e32 v151, v69
	v_mov_b32_e32 v152, v70
	v_mov_b32_e32 v153, v71
	v_mov_b32_e32 v154, v72
	v_mov_b32_e32 v155, v73
	v_mov_b32_e32 v156, v82
	v_mov_b32_e32 v157, v83
	v_mov_b32_e32 v158, v84
	v_mov_b32_e32 v159, v85
	v_mov_b32_e32 v160, v86
	v_mov_b32_e32 v161, v87
	v_mov_b32_e32 v162, v88
	v_mov_b32_e32 v163, v89
	v_mov_b32_e32 v164, v90
	v_mov_b32_e32 v165, v91
	v_mov_b32_e32 v166, v92
	v_mov_b32_e32 v167, v93
	v_mov_b32_e32 v168, v94
	v_mov_b32_e32 v169, v95
	v_mov_b32_e32 v170, v96
	v_mov_b32_e32 v171, v97
	v_mov_b32_e32 v174, v98
	v_mov_b32_e32 v175, v99
	v_mov_b32_e32 v176, v100
	v_mov_b32_e32 v177, v101
	v_mov_b32_e32 v182, v102
	v_mov_b32_e32 v183, v103
	v_mov_b32_e32 v184, v104
	v_mov_b32_e32 v185, v105
	v_mov_b32_e32 v188, v106
	v_mov_b32_e32 v189, v107
	v_mov_b32_e32 v190, v108
	v_mov_b32_e32 v191, v109
	v_mov_b32_e32 v192, v110
	v_mov_b32_e32 v193, v111
	v_mov_b32_e32 v194, v112
	v_mov_b32_e32 v195, v113
	v_mov_b32_e32 v208, v114
	v_mov_b32_e32 v209, v115
	v_mov_b32_e32 v210, v116
	v_mov_b32_e32 v211, v117
	v_mov_b32_e32 v212, v118
	v_mov_b32_e32 v213, v119
	v_mov_b32_e32 v214, v120
	v_mov_b32_e32 v215, v121
	v_mov_b32_e32 v216, v122
	v_mov_b32_e32 v217, v123
	v_mov_b32_e32 v218, v124
	v_mov_b32_e32 v219, v125
	v_mov_b32_e32 v220, v126
	v_mov_b32_e32 v221, v127
	v_mov_b32_e32 v222, v128
	v_mov_b32_e32 v223, v129
	v_mov_b32_e32 v242, v136
	v_mov_b32_e32 v243, v137
	v_mov_b32_e32 v244, v138
	v_mov_b32_e32 v245, v139
	v_mov_b32_e32 v199, v140
	v_mov_b32_e32 v206, v141
	v_mov_b32_e32 v207, v142
	v_mov_b32_e32 v226, v143
	s_add_i32 s48, s48, 1
	s_mov_b32 s39, 0
	v_readlane_b32 s30, v249, 0
	s_nop 0
	s_and_b32 s31, s30, 7
	s_lshr_b32 s30, s30, 3
	s_cmp_lt_u32 s30, 32
	s_cselect_b32 s35, 6, 5
	s_cmp_lt_u32 s48, s35
	s_cbranch_scc0 .Lf2_c1_extra
	s_lshl_b32 s33, s48, 6
	s_add_i32 s33, s33, s30
	s_cmp_ge_u32 s33, 0xb0
	s_cselect_b32 s34, 1, 0
	s_mul_i32 s36, s34, 0xb0
	s_sub_i32 s33, s33, s36
	s_lshr_b32 s37, s33, 2
	s_and_b32 s33, s33, 3
	s_lshl_b32 s34, s34, 3
	s_add_i32 s33, s33, s34
	s_lshl_b32 s33, s33, 3
	s_add_i32 s36, s33, s31
	s_add_i32 s38, s36, 32
	s_branch .Lf2_c1_have
